# v33 + adaLN GEMV weight rows streamed with LDS-DMA (global_load_lds nt) into a per-wave LDS ring
# speedup vs baseline: 1.0114x; 1.0114x over previous
; #define GAS __attribute__((address_space(1)))
; #define LAS __attribute__((address_space(3)))
; DI void phase_prologue(const Frame& F0, const Args& a) {
;     ...
;             if (F.lane < 48) {
;                 const int kb = F.wave * 256;
; #pragma unroll 16
;                 for (int k = 0; k < 256; ++k) {
;                     const f32x4 w = __builtin_nontemporal_load((const GAS f32x4*)(W + (size_t)(kb + k) * NADA + F.lane * 4));
;                     const float s0 = sv[kb + k], s1 = sv[DM + kb + k], s2 = sv[2 * DM + kb + k];
;                     acc0 += w * s0; acc1 += w * s1; acc2 += w * s2;
;                 }
;                 *(LAS f32x4*)(red + (F.wave * 3 + 0) * 192 + F.lane * 4) = acc0;
;                 *(LAS f32x4*)(red + (F.wave * 3 + 1) * 192 + F.lane * 4) = acc1;
;                 *(LAS f32x4*)(red + (F.wave * 3 + 2) * 192 + F.lane * 4) = acc2;
.LBB0_24:
	v_readfirstlane_b32 s92, v58
	v_readfirstlane_b32 s93, v59
	v_lshlrev_b32_e32 v95, 4, v78
	s_mul_i32 s94, s44, 0x3000
	s_add_i32 s94, s94, 0xa800
	v_add_u32_e32 v94, s94, v95
	s_nop 3
	s_mov_b32 m0, s94
	s_nop 0
	global_load_lds_dwordx4 v95, s[92:93] nt
	s_add_u32 s92, s92, 0xc000
	s_addc_u32 s93, s93, 0
	s_add_u32 m0, s94, 0x300
	s_nop 0
	global_load_lds_dwordx4 v95, s[92:93] nt
	s_add_u32 s92, s92, 0xc000
	s_addc_u32 s93, s93, 0
	s_add_u32 m0, s94, 0x600
	s_nop 0
	global_load_lds_dwordx4 v95, s[92:93] nt
	s_add_u32 s92, s92, 0xc000
	s_addc_u32 s93, s93, 0
	s_add_u32 m0, s94, 0x900
	s_nop 0
	global_load_lds_dwordx4 v95, s[92:93] nt
	s_add_u32 s92, s92, 0xc000
	s_addc_u32 s93, s93, 0
	s_add_u32 m0, s94, 0xc00
	s_nop 0
	global_load_lds_dwordx4 v95, s[92:93] nt
	s_add_u32 s92, s92, 0xc000
	s_addc_u32 s93, s93, 0
	s_add_u32 m0, s94, 0xf00
	s_nop 0
	global_load_lds_dwordx4 v95, s[92:93] nt
	s_add_u32 s92, s92, 0xc000
	s_addc_u32 s93, s93, 0
	s_add_u32 m0, s94, 0x1200
	s_nop 0
	global_load_lds_dwordx4 v95, s[92:93] nt
	s_add_u32 s92, s92, 0xc000
	s_addc_u32 s93, s93, 0
	s_add_u32 m0, s94, 0x1500
	s_nop 0
	global_load_lds_dwordx4 v95, s[92:93] nt
	s_add_u32 s92, s92, 0xc000
	s_addc_u32 s93, s93, 0
	s_add_u32 m0, s94, 0x1800
	s_nop 0
	global_load_lds_dwordx4 v95, s[92:93] nt
	s_add_u32 s92, s92, 0xc000
	s_addc_u32 s93, s93, 0
	s_add_u32 m0, s94, 0x1b00
	s_nop 0
	global_load_lds_dwordx4 v95, s[92:93] nt
	s_add_u32 s92, s92, 0xc000
	s_addc_u32 s93, s93, 0
	s_add_u32 m0, s94, 0x1e00
	s_nop 0
	global_load_lds_dwordx4 v95, s[92:93] nt
	s_add_u32 s92, s92, 0xc000
	s_addc_u32 s93, s93, 0
	s_add_u32 m0, s94, 0x2100
	s_nop 0
	global_load_lds_dwordx4 v95, s[92:93] nt
	s_add_u32 s92, s92, 0xc000
	s_addc_u32 s93, s93, 0
	s_add_u32 m0, s94, 0x2400
	s_nop 0
	global_load_lds_dwordx4 v95, s[92:93] nt
	s_add_u32 s92, s92, 0xc000
	s_addc_u32 s93, s93, 0
	s_add_u32 m0, s94, 0x2700
	s_nop 0
	global_load_lds_dwordx4 v95, s[92:93] nt
	s_add_u32 s92, s92, 0xc000
	s_addc_u32 s93, s93, 0
	s_add_u32 m0, s94, 0x2a00
	s_nop 0
	global_load_lds_dwordx4 v95, s[92:93] nt
	s_add_u32 s92, s92, 0xc000
	s_addc_u32 s93, s93, 0
	s_add_u32 m0, s94, 0x2d00
	s_nop 0
	global_load_lds_dwordx4 v95, s[92:93] nt
	s_add_u32 s92, s92, 0xc000
	s_addc_u32 s93, s93, 0
	s_movk_i32 s95, 15
.Lada_loop:
	v_mov_b32_e32 v93, s12
	ds_read_b128 v[160:163], v93
	ds_read_b128 v[164:167], v93 offset:16
	ds_read_b128 v[168:171], v93 offset:32
	ds_read_b128 v[172:175], v93 offset:48
	ds_read_b128 v[176:179], v93 offset:8192
	ds_read_b128 v[180:183], v93 offset:8208
	ds_read_b128 v[184:187], v93 offset:8224
	ds_read_b128 v[188:191], v93 offset:8240
	ds_read_b128 v[192:195], v93 offset:16384
	ds_read_b128 v[196:199], v93 offset:16400
	ds_read_b128 v[200:203], v93 offset:16416
	ds_read_b128 v[204:207], v93 offset:16432
	s_add_i32 s12, s12, 64
	s_waitcnt vmcnt(12)
	ds_read_b128 v[96:99], v94
	ds_read_b128 v[100:103], v94 offset:768
	ds_read_b128 v[104:107], v94 offset:1536
	ds_read_b128 v[108:111], v94 offset:2304
	s_waitcnt lgkmcnt(0)
	v_pk_fma_f32 v[6:7], v[96:97], v[160:161], v[6:7] op_sel_hi:[1,0,1]
	v_pk_fma_f32 v[8:9], v[98:99], v[160:161], v[8:9] op_sel_hi:[1,0,1]
	v_pk_fma_f32 v[10:11], v[96:97], v[176:177], v[10:11] op_sel_hi:[1,0,1]
	v_pk_fma_f32 v[12:13], v[98:99], v[176:177], v[12:13] op_sel_hi:[1,0,1]
	v_pk_fma_f32 v[14:15], v[96:97], v[192:193], v[14:15] op_sel_hi:[1,0,1]
	v_pk_fma_f32 v[16:17], v[98:99], v[192:193], v[16:17] op_sel_hi:[1,0,1]
	v_pk_fma_f32 v[6:7], v[100:101], v[160:161], v[6:7] op_sel:[0,1,0]
	v_pk_fma_f32 v[8:9], v[102:103], v[160:161], v[8:9] op_sel:[0,1,0]
	v_pk_fma_f32 v[10:11], v[100:101], v[176:177], v[10:11] op_sel:[0,1,0]
	v_pk_fma_f32 v[12:13], v[102:103], v[176:177], v[12:13] op_sel:[0,1,0]
	v_pk_fma_f32 v[14:15], v[100:101], v[192:193], v[14:15] op_sel:[0,1,0]
	v_pk_fma_f32 v[16:17], v[102:103], v[192:193], v[16:17] op_sel:[0,1,0]
	v_pk_fma_f32 v[6:7], v[104:105], v[162:163], v[6:7] op_sel_hi:[1,0,1]
	v_pk_fma_f32 v[8:9], v[106:107], v[162:163], v[8:9] op_sel_hi:[1,0,1]
	v_pk_fma_f32 v[10:11], v[104:105], v[178:179], v[10:11] op_sel_hi:[1,0,1]
	v_pk_fma_f32 v[12:13], v[106:107], v[178:179], v[12:13] op_sel_hi:[1,0,1]
	v_pk_fma_f32 v[14:15], v[104:105], v[194:195], v[14:15] op_sel_hi:[1,0,1]
	v_pk_fma_f32 v[16:17], v[106:107], v[194:195], v[16:17] op_sel_hi:[1,0,1]
	v_pk_fma_f32 v[6:7], v[108:109], v[162:163], v[6:7] op_sel:[0,1,0]
	v_pk_fma_f32 v[8:9], v[110:111], v[162:163], v[8:9] op_sel:[0,1,0]
	v_pk_fma_f32 v[10:11], v[108:109], v[178:179], v[10:11] op_sel:[0,1,0]
	v_pk_fma_f32 v[12:13], v[110:111], v[178:179], v[12:13] op_sel:[0,1,0]
	v_pk_fma_f32 v[14:15], v[108:109], v[194:195], v[14:15] op_sel:[0,1,0]
	v_pk_fma_f32 v[16:17], v[110:111], v[194:195], v[16:17] op_sel:[0,1,0]
	s_mov_b32 m0, s94
	s_nop 0
	global_load_lds_dwordx4 v95, s[92:93] nt
	s_add_u32 s92, s92, 0xc000
	s_addc_u32 s93, s93, 0
	s_add_u32 m0, s94, 0x300
	s_nop 0
	global_load_lds_dwordx4 v95, s[92:93] nt
	s_add_u32 s92, s92, 0xc000
	s_addc_u32 s93, s93, 0
	s_add_u32 m0, s94, 0x600
	s_nop 0
	global_load_lds_dwordx4 v95, s[92:93] nt
	s_add_u32 s92, s92, 0xc000
	s_addc_u32 s93, s93, 0
	s_add_u32 m0, s94, 0x900
	s_nop 0
	global_load_lds_dwordx4 v95, s[92:93] nt
	s_add_u32 s92, s92, 0xc000
	s_addc_u32 s93, s93, 0
	s_waitcnt vmcnt(12)
	ds_read_b128 v[112:115], v94 offset:3072
	ds_read_b128 v[116:119], v94 offset:3840
	ds_read_b128 v[120:123], v94 offset:4608
	ds_read_b128 v[124:127], v94 offset:5376
	s_waitcnt lgkmcnt(0)
; #define GAS __attribute__((address_space(1)))
; #define LAS __attribute__((address_space(3)))
; DI void phase_prologue(const Frame& F0, const Args& a) {
;     ...
;             if (F.lane < 48) {
;                 const int kb = F.wave * 256;
; #pragma unroll 16
;                 for (int k = 0; k < 256; ++k) {
;                     const f32x4 w = __builtin_nontemporal_load((const GAS f32x4*)(W + (size_t)(kb + k) * NADA + F.lane * 4));
;                     const float s0 = sv[kb + k], s1 = sv[DM + kb + k], s2 = sv[2 * DM + kb + k];
;                     acc0 += w * s0; acc1 += w * s1; acc2 += w * s2;
;                 }
;                 *(LAS f32x4*)(red + (F.wave * 3 + 0) * 192 + F.lane * 4) = acc0;
;                 *(LAS f32x4*)(red + (F.wave * 3 + 1) * 192 + F.lane * 4) = acc1;
;                 *(LAS f32x4*)(red + (F.wave * 3 + 2) * 192 + F.lane * 4) = acc2;
	v_pk_fma_f32 v[6:7], v[112:113], v[164:165], v[6:7] op_sel_hi:[1,0,1]
	v_pk_fma_f32 v[8:9], v[114:115], v[164:165], v[8:9] op_sel_hi:[1,0,1]
	v_pk_fma_f32 v[10:11], v[112:113], v[180:181], v[10:11] op_sel_hi:[1,0,1]
	v_pk_fma_f32 v[12:13], v[114:115], v[180:181], v[12:13] op_sel_hi:[1,0,1]
	v_pk_fma_f32 v[14:15], v[112:113], v[196:197], v[14:15] op_sel_hi:[1,0,1]
	v_pk_fma_f32 v[16:17], v[114:115], v[196:197], v[16:17] op_sel_hi:[1,0,1]
	v_pk_fma_f32 v[6:7], v[116:117], v[164:165], v[6:7] op_sel:[0,1,0]
	v_pk_fma_f32 v[8:9], v[118:119], v[164:165], v[8:9] op_sel:[0,1,0]
	v_pk_fma_f32 v[10:11], v[116:117], v[180:181], v[10:11] op_sel:[0,1,0]
	v_pk_fma_f32 v[12:13], v[118:119], v[180:181], v[12:13] op_sel:[0,1,0]
	v_pk_fma_f32 v[14:15], v[116:117], v[196:197], v[14:15] op_sel:[0,1,0]
	v_pk_fma_f32 v[16:17], v[118:119], v[196:197], v[16:17] op_sel:[0,1,0]
	v_pk_fma_f32 v[6:7], v[120:121], v[166:167], v[6:7] op_sel_hi:[1,0,1]
	v_pk_fma_f32 v[8:9], v[122:123], v[166:167], v[8:9] op_sel_hi:[1,0,1]
	v_pk_fma_f32 v[10:11], v[120:121], v[182:183], v[10:11] op_sel_hi:[1,0,1]
	v_pk_fma_f32 v[12:13], v[122:123], v[182:183], v[12:13] op_sel_hi:[1,0,1]
	v_pk_fma_f32 v[14:15], v[120:121], v[198:199], v[14:15] op_sel_hi:[1,0,1]
	v_pk_fma_f32 v[16:17], v[122:123], v[198:199], v[16:17] op_sel_hi:[1,0,1]
	v_pk_fma_f32 v[6:7], v[124:125], v[166:167], v[6:7] op_sel:[0,1,0]
	v_pk_fma_f32 v[8:9], v[126:127], v[166:167], v[8:9] op_sel:[0,1,0]
	v_pk_fma_f32 v[10:11], v[124:125], v[182:183], v[10:11] op_sel:[0,1,0]
	v_pk_fma_f32 v[12:13], v[126:127], v[182:183], v[12:13] op_sel:[0,1,0]
	v_pk_fma_f32 v[14:15], v[124:125], v[198:199], v[14:15] op_sel:[0,1,0]
	v_pk_fma_f32 v[16:17], v[126:127], v[198:199], v[16:17] op_sel:[0,1,0]
	s_add_u32 m0, s94, 0xc00
	s_nop 0
	global_load_lds_dwordx4 v95, s[92:93] nt
	s_add_u32 s92, s92, 0xc000
	s_addc_u32 s93, s93, 0
	s_add_u32 m0, s94, 0xf00
	s_nop 0
	global_load_lds_dwordx4 v95, s[92:93] nt
	s_add_u32 s92, s92, 0xc000
	s_addc_u32 s93, s93, 0
	s_add_u32 m0, s94, 0x1200
	s_nop 0
	global_load_lds_dwordx4 v95, s[92:93] nt
	s_add_u32 s92, s92, 0xc000
	s_addc_u32 s93, s93, 0
	s_add_u32 m0, s94, 0x1500
	s_nop 0
	global_load_lds_dwordx4 v95, s[92:93] nt
	s_add_u32 s92, s92, 0xc000
	s_addc_u32 s93, s93, 0
	s_waitcnt vmcnt(12)
	ds_read_b128 v[128:131], v94 offset:6144
	ds_read_b128 v[132:135], v94 offset:6912
	ds_read_b128 v[136:139], v94 offset:7680
	ds_read_b128 v[140:143], v94 offset:8448
	s_waitcnt lgkmcnt(0)
	v_pk_fma_f32 v[6:7], v[128:129], v[168:169], v[6:7] op_sel_hi:[1,0,1]
	v_pk_fma_f32 v[8:9], v[130:131], v[168:169], v[8:9] op_sel_hi:[1,0,1]
	v_pk_fma_f32 v[10:11], v[128:129], v[184:185], v[10:11] op_sel_hi:[1,0,1]
	v_pk_fma_f32 v[12:13], v[130:131], v[184:185], v[12:13] op_sel_hi:[1,0,1]
	v_pk_fma_f32 v[14:15], v[128:129], v[200:201], v[14:15] op_sel_hi:[1,0,1]
	v_pk_fma_f32 v[16:17], v[130:131], v[200:201], v[16:17] op_sel_hi:[1,0,1]
	v_pk_fma_f32 v[6:7], v[132:133], v[168:169], v[6:7] op_sel:[0,1,0]
	v_pk_fma_f32 v[8:9], v[134:135], v[168:169], v[8:9] op_sel:[0,1,0]
	v_pk_fma_f32 v[10:11], v[132:133], v[184:185], v[10:11] op_sel:[0,1,0]
	v_pk_fma_f32 v[12:13], v[134:135], v[184:185], v[12:13] op_sel:[0,1,0]
	v_pk_fma_f32 v[14:15], v[132:133], v[200:201], v[14:15] op_sel:[0,1,0]
	v_pk_fma_f32 v[16:17], v[134:135], v[200:201], v[16:17] op_sel:[0,1,0]
	v_pk_fma_f32 v[6:7], v[136:137], v[170:171], v[6:7] op_sel_hi:[1,0,1]
	v_pk_fma_f32 v[8:9], v[138:139], v[170:171], v[8:9] op_sel_hi:[1,0,1]
	v_pk_fma_f32 v[10:11], v[136:137], v[186:187], v[10:11] op_sel_hi:[1,0,1]
	v_pk_fma_f32 v[12:13], v[138:139], v[186:187], v[12:13] op_sel_hi:[1,0,1]
	v_pk_fma_f32 v[14:15], v[136:137], v[202:203], v[14:15] op_sel_hi:[1,0,1]
	v_pk_fma_f32 v[16:17], v[138:139], v[202:203], v[16:17] op_sel_hi:[1,0,1]
	v_pk_fma_f32 v[6:7], v[140:141], v[170:171], v[6:7] op_sel:[0,1,0]
	v_pk_fma_f32 v[8:9], v[142:143], v[170:171], v[8:9] op_sel:[0,1,0]
	v_pk_fma_f32 v[10:11], v[140:141], v[186:187], v[10:11] op_sel:[0,1,0]
	v_pk_fma_f32 v[12:13], v[142:143], v[186:187], v[12:13] op_sel:[0,1,0]
	v_pk_fma_f32 v[14:15], v[140:141], v[202:203], v[14:15] op_sel:[0,1,0]
	v_pk_fma_f32 v[16:17], v[142:143], v[202:203], v[16:17] op_sel:[0,1,0]
	s_add_u32 m0, s94, 0x1800
	s_nop 0
	global_load_lds_dwordx4 v95, s[92:93] nt
	s_add_u32 s92, s92, 0xc000
	s_addc_u32 s93, s93, 0
	s_add_u32 m0, s94, 0x1b00
	s_nop 0
	global_load_lds_dwordx4 v95, s[92:93] nt
	s_add_u32 s92, s92, 0xc000
	s_addc_u32 s93, s93, 0
	s_add_u32 m0, s94, 0x1e00
	s_nop 0
	global_load_lds_dwordx4 v95, s[92:93] nt
	s_add_u32 s92, s92, 0xc000
	s_addc_u32 s93, s93, 0
	s_add_u32 m0, s94, 0x2100
	s_nop 0
	global_load_lds_dwordx4 v95, s[92:93] nt
	s_add_u32 s92, s92, 0xc000
	s_addc_u32 s93, s93, 0
	s_waitcnt vmcnt(12)
	ds_read_b128 v[144:147], v94 offset:9216
	ds_read_b128 v[148:151], v94 offset:9984
	ds_read_b128 v[152:155], v94 offset:10752
	ds_read_b128 v[156:159], v94 offset:11520
	s_waitcnt lgkmcnt(0)
; #define GAS __attribute__((address_space(1)))
; #define LAS __attribute__((address_space(3)))
; DI void phase_prologue(const Frame& F0, const Args& a) {
;     ...
;             if (F.lane < 48) {
;                 const int kb = F.wave * 256;
; #pragma unroll 16
;                 for (int k = 0; k < 256; ++k) {
;                     const f32x4 w = __builtin_nontemporal_load((const GAS f32x4*)(W + (size_t)(kb + k) * NADA + F.lane * 4));
;                     const float s0 = sv[kb + k], s1 = sv[DM + kb + k], s2 = sv[2 * DM + kb + k];
;                     acc0 += w * s0; acc1 += w * s1; acc2 += w * s2;
;                 }
;                 *(LAS f32x4*)(red + (F.wave * 3 + 0) * 192 + F.lane * 4) = acc0;
;                 *(LAS f32x4*)(red + (F.wave * 3 + 1) * 192 + F.lane * 4) = acc1;
;                 *(LAS f32x4*)(red + (F.wave * 3 + 2) * 192 + F.lane * 4) = acc2;
	v_pk_fma_f32 v[6:7], v[144:145], v[172:173], v[6:7] op_sel_hi:[1,0,1]
	v_pk_fma_f32 v[8:9], v[146:147], v[172:173], v[8:9] op_sel_hi:[1,0,1]
	v_pk_fma_f32 v[10:11], v[144:145], v[188:189], v[10:11] op_sel_hi:[1,0,1]
	v_pk_fma_f32 v[12:13], v[146:147], v[188:189], v[12:13] op_sel_hi:[1,0,1]
	v_pk_fma_f32 v[14:15], v[144:145], v[204:205], v[14:15] op_sel_hi:[1,0,1]
	v_pk_fma_f32 v[16:17], v[146:147], v[204:205], v[16:17] op_sel_hi:[1,0,1]
	v_pk_fma_f32 v[6:7], v[148:149], v[172:173], v[6:7] op_sel:[0,1,0]
	v_pk_fma_f32 v[8:9], v[150:151], v[172:173], v[8:9] op_sel:[0,1,0]
	v_pk_fma_f32 v[10:11], v[148:149], v[188:189], v[10:11] op_sel:[0,1,0]
	v_pk_fma_f32 v[12:13], v[150:151], v[188:189], v[12:13] op_sel:[0,1,0]
	v_pk_fma_f32 v[14:15], v[148:149], v[204:205], v[14:15] op_sel:[0,1,0]
	v_pk_fma_f32 v[16:17], v[150:151], v[204:205], v[16:17] op_sel:[0,1,0]
	v_pk_fma_f32 v[6:7], v[152:153], v[174:175], v[6:7] op_sel_hi:[1,0,1]
	v_pk_fma_f32 v[8:9], v[154:155], v[174:175], v[8:9] op_sel_hi:[1,0,1]
	v_pk_fma_f32 v[10:11], v[152:153], v[190:191], v[10:11] op_sel_hi:[1,0,1]
	v_pk_fma_f32 v[12:13], v[154:155], v[190:191], v[12:13] op_sel_hi:[1,0,1]
	v_pk_fma_f32 v[14:15], v[152:153], v[206:207], v[14:15] op_sel_hi:[1,0,1]
	v_pk_fma_f32 v[16:17], v[154:155], v[206:207], v[16:17] op_sel_hi:[1,0,1]
	v_pk_fma_f32 v[6:7], v[156:157], v[174:175], v[6:7] op_sel:[0,1,0]
	v_pk_fma_f32 v[8:9], v[158:159], v[174:175], v[8:9] op_sel:[0,1,0]
	v_pk_fma_f32 v[10:11], v[156:157], v[190:191], v[10:11] op_sel:[0,1,0]
	v_pk_fma_f32 v[12:13], v[158:159], v[190:191], v[12:13] op_sel:[0,1,0]
	v_pk_fma_f32 v[14:15], v[156:157], v[206:207], v[14:15] op_sel:[0,1,0]
	v_pk_fma_f32 v[16:17], v[158:159], v[206:207], v[16:17] op_sel:[0,1,0]
	s_add_u32 m0, s94, 0x2400
	s_nop 0
	global_load_lds_dwordx4 v95, s[92:93] nt
	s_add_u32 s92, s92, 0xc000
	s_addc_u32 s93, s93, 0
	s_add_u32 m0, s94, 0x2700
	s_nop 0
	global_load_lds_dwordx4 v95, s[92:93] nt
	s_add_u32 s92, s92, 0xc000
	s_addc_u32 s93, s93, 0
	s_add_u32 m0, s94, 0x2a00
	s_nop 0
	global_load_lds_dwordx4 v95, s[92:93] nt
	s_add_u32 s92, s92, 0xc000
	s_addc_u32 s93, s93, 0
	s_add_u32 m0, s94, 0x2d00
	s_nop 0
	global_load_lds_dwordx4 v95, s[92:93] nt
	s_add_u32 s92, s92, 0xc000
	s_addc_u32 s93, s93, 0
	s_add_i32 s95, s95, -1
	s_cmp_lg_u32 s95, 0
	s_cbranch_scc1 .Lada_loop
	v_mov_b32_e32 v93, s12
	ds_read_b128 v[160:163], v93
	ds_read_b128 v[164:167], v93 offset:16
	ds_read_b128 v[168:171], v93 offset:32
	ds_read_b128 v[172:175], v93 offset:48
	ds_read_b128 v[176:179], v93 offset:8192
	ds_read_b128 v[180:183], v93 offset:8208
	ds_read_b128 v[184:187], v93 offset:8224
	ds_read_b128 v[188:191], v93 offset:8240
	ds_read_b128 v[192:195], v93 offset:16384
	ds_read_b128 v[196:199], v93 offset:16400
	ds_read_b128 v[200:203], v93 offset:16416
	ds_read_b128 v[204:207], v93 offset:16432
	s_add_i32 s12, s12, 64
	s_waitcnt vmcnt(12)
	ds_read_b128 v[96:99], v94
	ds_read_b128 v[100:103], v94 offset:768
	ds_read_b128 v[104:107], v94 offset:1536
	ds_read_b128 v[108:111], v94 offset:2304
	s_waitcnt lgkmcnt(0)
	v_pk_fma_f32 v[6:7], v[96:97], v[160:161], v[6:7] op_sel_hi:[1,0,1]
	v_pk_fma_f32 v[8:9], v[98:99], v[160:161], v[8:9] op_sel_hi:[1,0,1]
	v_pk_fma_f32 v[10:11], v[96:97], v[176:177], v[10:11] op_sel_hi:[1,0,1]
	v_pk_fma_f32 v[12:13], v[98:99], v[176:177], v[12:13] op_sel_hi:[1,0,1]
	v_pk_fma_f32 v[14:15], v[96:97], v[192:193], v[14:15] op_sel_hi:[1,0,1]
	v_pk_fma_f32 v[16:17], v[98:99], v[192:193], v[16:17] op_sel_hi:[1,0,1]
	v_pk_fma_f32 v[6:7], v[100:101], v[160:161], v[6:7] op_sel:[0,1,0]
	v_pk_fma_f32 v[8:9], v[102:103], v[160:161], v[8:9] op_sel:[0,1,0]
	v_pk_fma_f32 v[10:11], v[100:101], v[176:177], v[10:11] op_sel:[0,1,0]
	v_pk_fma_f32 v[12:13], v[102:103], v[176:177], v[12:13] op_sel:[0,1,0]
	v_pk_fma_f32 v[14:15], v[100:101], v[192:193], v[14:15] op_sel:[0,1,0]
	v_pk_fma_f32 v[16:17], v[102:103], v[192:193], v[16:17] op_sel:[0,1,0]
	v_pk_fma_f32 v[6:7], v[104:105], v[162:163], v[6:7] op_sel_hi:[1,0,1]
	v_pk_fma_f32 v[8:9], v[106:107], v[162:163], v[8:9] op_sel_hi:[1,0,1]
	v_pk_fma_f32 v[10:11], v[104:105], v[178:179], v[10:11] op_sel_hi:[1,0,1]
	v_pk_fma_f32 v[12:13], v[106:107], v[178:179], v[12:13] op_sel_hi:[1,0,1]
	v_pk_fma_f32 v[14:15], v[104:105], v[194:195], v[14:15] op_sel_hi:[1,0,1]
	v_pk_fma_f32 v[16:17], v[106:107], v[194:195], v[16:17] op_sel_hi:[1,0,1]
	v_pk_fma_f32 v[6:7], v[108:109], v[162:163], v[6:7] op_sel:[0,1,0]
	v_pk_fma_f32 v[8:9], v[110:111], v[162:163], v[8:9] op_sel:[0,1,0]
	v_pk_fma_f32 v[10:11], v[108:109], v[178:179], v[10:11] op_sel:[0,1,0]
	v_pk_fma_f32 v[12:13], v[110:111], v[178:179], v[12:13] op_sel:[0,1,0]
	v_pk_fma_f32 v[14:15], v[108:109], v[194:195], v[14:15] op_sel:[0,1,0]
	v_pk_fma_f32 v[16:17], v[110:111], v[194:195], v[16:17] op_sel:[0,1,0]
	s_waitcnt vmcnt(8)
	ds_read_b128 v[112:115], v94 offset:3072
	ds_read_b128 v[116:119], v94 offset:3840
	ds_read_b128 v[120:123], v94 offset:4608
	ds_read_b128 v[124:127], v94 offset:5376
	s_waitcnt lgkmcnt(0)
; #define GAS __attribute__((address_space(1)))
; #define LAS __attribute__((address_space(3)))
; DI void phase_prologue(const Frame& F0, const Args& a) {
;     ...
;             if (F.lane < 48) {
;                 const int kb = F.wave * 256;
; #pragma unroll 16
;                 for (int k = 0; k < 256; ++k) {
;                     const f32x4 w = __builtin_nontemporal_load((const GAS f32x4*)(W + (size_t)(kb + k) * NADA + F.lane * 4));
;                     const float s0 = sv[kb + k], s1 = sv[DM + kb + k], s2 = sv[2 * DM + kb + k];
;                     acc0 += w * s0; acc1 += w * s1; acc2 += w * s2;
;                 }
;                 *(LAS f32x4*)(red + (F.wave * 3 + 0) * 192 + F.lane * 4) = acc0;
;                 *(LAS f32x4*)(red + (F.wave * 3 + 1) * 192 + F.lane * 4) = acc1;
;                 *(LAS f32x4*)(red + (F.wave * 3 + 2) * 192 + F.lane * 4) = acc2;
	v_pk_fma_f32 v[6:7], v[112:113], v[164:165], v[6:7] op_sel_hi:[1,0,1]
	v_pk_fma_f32 v[8:9], v[114:115], v[164:165], v[8:9] op_sel_hi:[1,0,1]
	v_pk_fma_f32 v[10:11], v[112:113], v[180:181], v[10:11] op_sel_hi:[1,0,1]
	v_pk_fma_f32 v[12:13], v[114:115], v[180:181], v[12:13] op_sel_hi:[1,0,1]
	v_pk_fma_f32 v[14:15], v[112:113], v[196:197], v[14:15] op_sel_hi:[1,0,1]
	v_pk_fma_f32 v[16:17], v[114:115], v[196:197], v[16:17] op_sel_hi:[1,0,1]
	v_pk_fma_f32 v[6:7], v[116:117], v[164:165], v[6:7] op_sel:[0,1,0]
	v_pk_fma_f32 v[8:9], v[118:119], v[164:165], v[8:9] op_sel:[0,1,0]
	v_pk_fma_f32 v[10:11], v[116:117], v[180:181], v[10:11] op_sel:[0,1,0]
	v_pk_fma_f32 v[12:13], v[118:119], v[180:181], v[12:13] op_sel:[0,1,0]
	v_pk_fma_f32 v[14:15], v[116:117], v[196:197], v[14:15] op_sel:[0,1,0]
	v_pk_fma_f32 v[16:17], v[118:119], v[196:197], v[16:17] op_sel:[0,1,0]
	v_pk_fma_f32 v[6:7], v[120:121], v[166:167], v[6:7] op_sel_hi:[1,0,1]
	v_pk_fma_f32 v[8:9], v[122:123], v[166:167], v[8:9] op_sel_hi:[1,0,1]
	v_pk_fma_f32 v[10:11], v[120:121], v[182:183], v[10:11] op_sel_hi:[1,0,1]
	v_pk_fma_f32 v[12:13], v[122:123], v[182:183], v[12:13] op_sel_hi:[1,0,1]
	v_pk_fma_f32 v[14:15], v[120:121], v[198:199], v[14:15] op_sel_hi:[1,0,1]
	v_pk_fma_f32 v[16:17], v[122:123], v[198:199], v[16:17] op_sel_hi:[1,0,1]
	v_pk_fma_f32 v[6:7], v[124:125], v[166:167], v[6:7] op_sel:[0,1,0]
	v_pk_fma_f32 v[8:9], v[126:127], v[166:167], v[8:9] op_sel:[0,1,0]
	v_pk_fma_f32 v[10:11], v[124:125], v[182:183], v[10:11] op_sel:[0,1,0]
	v_pk_fma_f32 v[12:13], v[126:127], v[182:183], v[12:13] op_sel:[0,1,0]
	v_pk_fma_f32 v[14:15], v[124:125], v[198:199], v[14:15] op_sel:[0,1,0]
	v_pk_fma_f32 v[16:17], v[126:127], v[198:199], v[16:17] op_sel:[0,1,0]
	s_waitcnt vmcnt(4)
	ds_read_b128 v[128:131], v94 offset:6144
	ds_read_b128 v[132:135], v94 offset:6912
	ds_read_b128 v[136:139], v94 offset:7680
	ds_read_b128 v[140:143], v94 offset:8448
	s_waitcnt lgkmcnt(0)
	v_pk_fma_f32 v[6:7], v[128:129], v[168:169], v[6:7] op_sel_hi:[1,0,1]
	v_pk_fma_f32 v[8:9], v[130:131], v[168:169], v[8:9] op_sel_hi:[1,0,1]
	v_pk_fma_f32 v[10:11], v[128:129], v[184:185], v[10:11] op_sel_hi:[1,0,1]
	v_pk_fma_f32 v[12:13], v[130:131], v[184:185], v[12:13] op_sel_hi:[1,0,1]
	v_pk_fma_f32 v[14:15], v[128:129], v[200:201], v[14:15] op_sel_hi:[1,0,1]
	v_pk_fma_f32 v[16:17], v[130:131], v[200:201], v[16:17] op_sel_hi:[1,0,1]
	v_pk_fma_f32 v[6:7], v[132:133], v[168:169], v[6:7] op_sel:[0,1,0]
	v_pk_fma_f32 v[8:9], v[134:135], v[168:169], v[8:9] op_sel:[0,1,0]
	v_pk_fma_f32 v[10:11], v[132:133], v[184:185], v[10:11] op_sel:[0,1,0]
	v_pk_fma_f32 v[12:13], v[134:135], v[184:185], v[12:13] op_sel:[0,1,0]
	v_pk_fma_f32 v[14:15], v[132:133], v[200:201], v[14:15] op_sel:[0,1,0]
	v_pk_fma_f32 v[16:17], v[134:135], v[200:201], v[16:17] op_sel:[0,1,0]
	v_pk_fma_f32 v[6:7], v[136:137], v[170:171], v[6:7] op_sel_hi:[1,0,1]
	v_pk_fma_f32 v[8:9], v[138:139], v[170:171], v[8:9] op_sel_hi:[1,0,1]
	v_pk_fma_f32 v[10:11], v[136:137], v[186:187], v[10:11] op_sel_hi:[1,0,1]
	v_pk_fma_f32 v[12:13], v[138:139], v[186:187], v[12:13] op_sel_hi:[1,0,1]
	v_pk_fma_f32 v[14:15], v[136:137], v[202:203], v[14:15] op_sel_hi:[1,0,1]
	v_pk_fma_f32 v[16:17], v[138:139], v[202:203], v[16:17] op_sel_hi:[1,0,1]
	v_pk_fma_f32 v[6:7], v[140:141], v[170:171], v[6:7] op_sel:[0,1,0]
	v_pk_fma_f32 v[8:9], v[142:143], v[170:171], v[8:9] op_sel:[0,1,0]
	v_pk_fma_f32 v[10:11], v[140:141], v[186:187], v[10:11] op_sel:[0,1,0]
	v_pk_fma_f32 v[12:13], v[142:143], v[186:187], v[12:13] op_sel:[0,1,0]
	v_pk_fma_f32 v[14:15], v[140:141], v[202:203], v[14:15] op_sel:[0,1,0]
	v_pk_fma_f32 v[16:17], v[142:143], v[202:203], v[16:17] op_sel:[0,1,0]
	s_waitcnt vmcnt(0)
	ds_read_b128 v[144:147], v94 offset:9216
	ds_read_b128 v[148:151], v94 offset:9984
	ds_read_b128 v[152:155], v94 offset:10752
	ds_read_b128 v[156:159], v94 offset:11520
	s_waitcnt lgkmcnt(0)
	v_pk_fma_f32 v[6:7], v[144:145], v[172:173], v[6:7] op_sel_hi:[1,0,1]
	v_pk_fma_f32 v[8:9], v[146:147], v[172:173], v[8:9] op_sel_hi:[1,0,1]
	v_pk_fma_f32 v[10:11], v[144:145], v[188:189], v[10:11] op_sel_hi:[1,0,1]
	v_pk_fma_f32 v[12:13], v[146:147], v[188:189], v[12:13] op_sel_hi:[1,0,1]
	v_pk_fma_f32 v[14:15], v[144:145], v[204:205], v[14:15] op_sel_hi:[1,0,1]
	v_pk_fma_f32 v[16:17], v[146:147], v[204:205], v[16:17] op_sel_hi:[1,0,1]
	v_pk_fma_f32 v[6:7], v[148:149], v[172:173], v[6:7] op_sel:[0,1,0]
	v_pk_fma_f32 v[8:9], v[150:151], v[172:173], v[8:9] op_sel:[0,1,0]
	v_pk_fma_f32 v[10:11], v[148:149], v[188:189], v[10:11] op_sel:[0,1,0]
	v_pk_fma_f32 v[12:13], v[150:151], v[188:189], v[12:13] op_sel:[0,1,0]
	v_pk_fma_f32 v[14:15], v[148:149], v[204:205], v[14:15] op_sel:[0,1,0]
	v_pk_fma_f32 v[16:17], v[150:151], v[204:205], v[16:17] op_sel:[0,1,0]
	v_pk_fma_f32 v[6:7], v[152:153], v[174:175], v[6:7] op_sel_hi:[1,0,1]
	v_pk_fma_f32 v[8:9], v[154:155], v[174:175], v[8:9] op_sel_hi:[1,0,1]
	v_pk_fma_f32 v[10:11], v[152:153], v[190:191], v[10:11] op_sel_hi:[1,0,1]
	v_pk_fma_f32 v[12:13], v[154:155], v[190:191], v[12:13] op_sel_hi:[1,0,1]
	v_pk_fma_f32 v[14:15], v[152:153], v[206:207], v[14:15] op_sel_hi:[1,0,1]
	v_pk_fma_f32 v[16:17], v[154:155], v[206:207], v[16:17] op_sel_hi:[1,0,1]
	v_pk_fma_f32 v[6:7], v[156:157], v[174:175], v[6:7] op_sel:[0,1,0]
	v_pk_fma_f32 v[8:9], v[158:159], v[174:175], v[8:9] op_sel:[0,1,0]
	v_pk_fma_f32 v[10:11], v[156:157], v[190:191], v[10:11] op_sel:[0,1,0]
	v_pk_fma_f32 v[12:13], v[158:159], v[190:191], v[12:13] op_sel:[0,1,0]
	v_pk_fma_f32 v[14:15], v[156:157], v[206:207], v[14:15] op_sel:[0,1,0]
	v_pk_fma_f32 v[16:17], v[158:159], v[206:207], v[16:17] op_sel:[0,1,0]
	ds_write_b128 v79, v[6:9] offset:24576
	ds_write_b128 v79, v[10:13] offset:25344
	ds_write_b128 v79, v[14:17] offset:26112
